# non-temporal loads for the once-read f32 weights in the per-layer weight conversion (on top of v42 K-loop placement)
# speedup vs baseline: 1.0541x; 1.0014x over previous
; __device__ __forceinline__ void conv_tile(const float* __restrict__ src, int ld, int col0, int nvalid, int K, u16* __restrict__ dst,
;                           int tile, float* T) {
;   const int ktiles = K >> 6;
;   const int kt = tile % ktiles, nt = tile / ktiles;
;   const int k0 = kt * 64, n0 = nt * 64;
;   const int tid = TID(), tx = tid & 63, ty = tid >> 6;
;   __syncthreads();
;   float tv[16];
; #pragma unroll
;   for (int r = 0; r < 16; r++) {
;     tv[r] = 0.f;
;     if (n0 + tx < nvalid) tv[r] = src[(size_t)(k0 + ty + 4 * r) * ld + col0 + n0 + tx];
;   }
; #pragma unroll
;   for (int r = 0; r < 16; r++) T[(ty + 4 * r) * 65 + tx] = tv[r];
;   __syncthreads();
; __device__ __forceinline__ void convert_weights(const Params& P, int l, float* T) {
;     ...
;     else conv_tile(P.s5_glu_w + (size_t)l * 256 * 256, 256, 0, 256, 256, (u16*)(ws + O_WGLU), t - c8, T);
.LBB0_2431:
	s_cmpk_gt_i32 s59, 0x27f
	s_cbranch_scc0 .LBB0_2440
	s_cmpk_gt_u32 s59, 0x67f
	s_cbranch_scc0 .LBB0_2441
	s_cmpk_gt_u32 s59, 0x77f
	s_cbranch_scc0 .LBB0_2442
	s_cmpk_gt_u32 s59, 0x87f
	s_cbranch_scc0 .LBB0_2443
	s_cmpk_gt_u32 s59, 0xc7f
	s_cbranch_scc0 .LBB0_2444
	s_cmpk_gt_u32 s59, 0x107f
	s_cbranch_scc0 .LBB0_2445
	s_cmpk_gt_u32 s59, 0x1097
	s_cbranch_scc0 .LBB0_2446
	s_cmpk_gt_u32 s59, 0x10a7
	s_cbranch_scc0 .LBB0_2447
	s_add_i32 s0, s52, 0x580
	s_and_b32 s0, s0, 0xfc0
	v_mov_b32_e32 v2, v169
	s_and_b32 s1, s53, 0xc0
	s_lshl_b32 s2, s0, 2
	v_ashrrev_i32_e32 v3, 6, v2
	v_add_u32_e32 v0, s1, v3
	s_add_u32 s2, s27, s2
	v_lshlrev_b32_e32 v1, 2, v2
	s_addc_u32 s3, s28, 0
	v_and_b32_e32 v130, 0xfc, v1
	v_ashrrev_i32_e32 v1, 31, v0
	v_lshl_add_u64 v[4:5], s[2:3], 0, v[130:131]
	v_lshlrev_b64 v[0:1], 10, v[0:1]
	v_lshl_add_u64 v[0:1], v[4:5], 0, v[0:1]
	v_add_co_u32_e32 v4, vcc, s63, v0
	s_nop 1
	v_addc_co_u32_e32 v5, vcc, 0, v1, vcc
	s_barrier
	global_load_dword v6, v[0:1], off nt
	global_load_dword v7, v[4:5], off offset:-4096 nt
	global_load_dword v8, v[4:5], off nt
	v_add_co_u32_e32 v4, vcc, s61, v0
	s_movk_i32 s2, 0x6000
	s_nop 0
	v_addc_co_u32_e32 v5, vcc, 0, v1, vcc
	global_load_dword v9, v[4:5], off offset:-4096 nt
	global_load_dword v10, v[4:5], off nt
	v_add_co_u32_e32 v4, vcc, s2, v0
	s_mov_b32 s2, 0x8000
	s_nop 0
	v_addc_co_u32_e32 v5, vcc, 0, v1, vcc
	global_load_dword v11, v[4:5], off offset:-4096 nt
	global_load_dword v12, v[4:5], off nt
	v_add_co_u32_e32 v4, vcc, s2, v0
	s_mov_b32 s2, 0xa000
	s_nop 0
	v_addc_co_u32_e32 v5, vcc, 0, v1, vcc
	global_load_dword v13, v[4:5], off offset:-4096 nt
	global_load_dword v14, v[4:5], off nt
	v_add_co_u32_e32 v4, vcc, s2, v0
	s_mov_b32 s2, 0xc000
	s_nop 0
	v_addc_co_u32_e32 v5, vcc, 0, v1, vcc
	global_load_dword v15, v[4:5], off offset:-4096 nt
	global_load_dword v16, v[4:5], off nt
	v_add_co_u32_e32 v4, vcc, s2, v0
	s_mov_b32 s2, 0xe000
	s_nop 0
	v_addc_co_u32_e32 v5, vcc, 0, v1, vcc
	global_load_dword v17, v[4:5], off offset:-4096 nt
	global_load_dword v18, v[4:5], off nt
	v_add_co_u32_e32 v4, vcc, s2, v0
	s_mov_b32 s2, 0xf000
	s_nop 0
	v_addc_co_u32_e32 v5, vcc, 0, v1, vcc
	global_load_dword v19, v[4:5], off offset:-4096 nt
	s_nop 0
	global_load_dword v4, v[4:5], off nt
	v_add_co_u32_e32 v0, vcc, s2, v0
	s_movk_i32 s2, 0x104
	s_nop 0
	v_addc_co_u32_e32 v1, vcc, 0, v1, vcc
	global_load_dword v5, v[0:1], off nt
	v_mad_u64_u32 v[0:1], s[2:3], v3, s2, v[130:131]
	s_lshl_b32 s1, s1, 1
	s_add_u32 s2, s10, s1
	s_addc_u32 s3, s11, 0
	s_waitcnt vmcnt(15)
	ds_write_b32 v0, v6
	s_waitcnt vmcnt(14)
	ds_write_b32 v0, v7 offset:1040
	s_waitcnt vmcnt(13)
	ds_write_b32 v0, v8 offset:2080
	s_waitcnt vmcnt(12)
	ds_write_b32 v0, v9 offset:3120
	s_waitcnt vmcnt(11)
	ds_write_b32 v0, v10 offset:4160
	s_waitcnt vmcnt(10)
	ds_write_b32 v0, v11 offset:5200
	s_waitcnt vmcnt(9)
	ds_write_b32 v0, v12 offset:6240
	s_waitcnt vmcnt(8)
	ds_write_b32 v0, v13 offset:7280
	s_waitcnt vmcnt(7)
	ds_write_b32 v0, v14 offset:8320
	s_waitcnt vmcnt(6)
	ds_write_b32 v0, v15 offset:9360
	s_waitcnt vmcnt(5)
	ds_write_b32 v0, v16 offset:10400
	s_waitcnt vmcnt(4)
	ds_write_b32 v0, v17 offset:11440
	s_waitcnt vmcnt(3)
	ds_write_b32 v0, v18 offset:12480
	s_waitcnt vmcnt(2)
	ds_write_b32 v0, v19 offset:13520
	s_waitcnt vmcnt(1)
	ds_write_b32 v0, v4 offset:14560
	s_waitcnt vmcnt(0)
	ds_write_b32 v0, v5 offset:15600
	s_waitcnt lgkmcnt(0)
	s_barrier
	s_mov_b64 s[4:5], 9
	s_cbranch_execz .LBB0_2448
	s_branch .LBB0_2449

; __device__ __forceinline__ void conv_tile(const float* __restrict__ src, int ld, int col0, int nvalid, int K, u16* __restrict__ dst,
;                           int tile, float* T) {
;   const int ktiles = K >> 6;
;   const int kt = tile % ktiles, nt = tile / ktiles;
;   const int k0 = kt * 64, n0 = nt * 64;
;   const int tid = TID(), tx = tid & 63, ty = tid >> 6;
;   __syncthreads();
;   float tv[16];
; #pragma unroll
;   for (int r = 0; r < 16; r++) {
;     tv[r] = 0.f;
;     if (n0 + tx < nvalid) tv[r] = src[(size_t)(k0 + ty + 4 * r) * ld + col0 + n0 + tx];
;   }
; #pragma unroll
;   for (int r = 0; r < 16; r++) T[(ty + 4 * r) * 65 + tx] = tv[r];
;   __syncthreads();
; __device__ __forceinline__ void convert_weights(const Params& P, int l, float* T) {
;     ...
;     else if (t < c8) conv_tile(P.mla_w_ukv + (size_t)l * 128 * 512, 512, 0, 512, 128, (u16*)(ws + O_WUKV), t - c7, T);
.LBB0_2448:
	s_and_b32 s0, s51, 0x1fc0
	v_mov_b32_e32 v2, v169
	s_and_b32 s1, s53, 64
	s_lshl_b32 s2, s0, 2
	v_ashrrev_i32_e32 v3, 6, v2
	v_add_u32_e32 v0, s1, v3
	s_add_u32 s2, s29, s2
	v_lshlrev_b32_e32 v1, 2, v2
	s_addc_u32 s3, s30, 0
	v_and_b32_e32 v130, 0xfc, v1
	v_ashrrev_i32_e32 v1, 31, v0
	v_lshl_add_u64 v[4:5], s[2:3], 0, v[130:131]
	v_lshlrev_b64 v[0:1], 11, v[0:1]
	v_lshl_add_u64 v[0:1], v[4:5], 0, v[0:1]
	v_add_co_u32_e32 v4, vcc, s63, v0
	s_nop 1
	v_addc_co_u32_e32 v5, vcc, 0, v1, vcc
	s_barrier
	global_load_dword v6, v[0:1], off nt
	global_load_dword v7, v[4:5], off nt
	v_add_co_u32_e32 v4, vcc, s61, v0
	s_movk_i32 s2, 0x6000
	s_nop 0
	v_addc_co_u32_e32 v5, vcc, 0, v1, vcc
	global_load_dword v8, v[4:5], off nt
	v_add_co_u32_e32 v4, vcc, s2, v0
	s_mov_b32 s2, 0x8000
	s_nop 0
	v_addc_co_u32_e32 v5, vcc, 0, v1, vcc
	global_load_dword v9, v[4:5], off nt
	v_add_co_u32_e32 v4, vcc, s2, v0
	s_mov_b32 s2, 0xa000
	s_nop 0
	v_addc_co_u32_e32 v5, vcc, 0, v1, vcc
	global_load_dword v10, v[4:5], off nt
	v_add_co_u32_e32 v4, vcc, s2, v0
	s_mov_b32 s2, 0xc000
	s_nop 0
	v_addc_co_u32_e32 v5, vcc, 0, v1, vcc
	global_load_dword v11, v[4:5], off nt
	v_add_co_u32_e32 v4, vcc, s2, v0
	s_mov_b32 s2, 0xe000
	s_nop 0
	v_addc_co_u32_e32 v5, vcc, 0, v1, vcc
	global_load_dword v12, v[4:5], off nt
	v_add_co_u32_e32 v4, vcc, s2, v0
	s_mov_b32 s2, 0x12000
	s_nop 0
	v_addc_co_u32_e32 v5, vcc, 0, v1, vcc
	global_load_dword v13, v[4:5], off nt
	v_add_co_u32_e32 v4, vcc, s33, v0
	s_lshl_b32 s1, s1, 1
	s_nop 0
	v_addc_co_u32_e32 v5, vcc, 0, v1, vcc
	global_load_dword v14, v[4:5], off nt
	v_add_co_u32_e32 v4, vcc, s2, v0
	s_mov_b32 s2, 0x14000
	s_nop 0
	v_addc_co_u32_e32 v5, vcc, 0, v1, vcc
	global_load_dword v15, v[4:5], off nt
	v_add_co_u32_e32 v4, vcc, s2, v0
	s_mov_b32 s2, 0x16000
	s_nop 0
	v_addc_co_u32_e32 v5, vcc, 0, v1, vcc
	global_load_dword v16, v[4:5], off nt
	v_add_co_u32_e32 v4, vcc, s2, v0
	s_mov_b32 s2, 0x18000
	s_nop 0
	v_addc_co_u32_e32 v5, vcc, 0, v1, vcc
	global_load_dword v17, v[4:5], off nt
	v_add_co_u32_e32 v4, vcc, s2, v0
	s_mov_b32 s2, 0x1a000
	s_nop 0
	v_addc_co_u32_e32 v5, vcc, 0, v1, vcc
	global_load_dword v18, v[4:5], off nt
	v_add_co_u32_e32 v4, vcc, s2, v0
	s_mov_b32 s2, 0x1c000
	s_nop 0
	v_addc_co_u32_e32 v5, vcc, 0, v1, vcc
	global_load_dword v19, v[4:5], off nt
	v_add_co_u32_e32 v4, vcc, s2, v0
	s_mov_b32 s2, 0x1e000
	s_nop 0
	v_addc_co_u32_e32 v5, vcc, 0, v1, vcc
	v_add_co_u32_e32 v0, vcc, s2, v0
	global_load_dword v4, v[4:5], off nt
	s_nop 0
	v_addc_co_u32_e32 v1, vcc, 0, v1, vcc
	global_load_dword v5, v[0:1], off nt
	s_movk_i32 s2, 0x104
	v_mad_u64_u32 v[0:1], s[2:3], v3, s2, v[130:131]
	s_add_u32 s2, s12, s1
	s_addc_u32 s3, s13, 0
	s_mov_b64 s[4:5], 8
	s_waitcnt vmcnt(15)
	ds_write_b32 v0, v6
	s_waitcnt vmcnt(14)
	ds_write_b32 v0, v7 offset:1040
	s_waitcnt vmcnt(13)
	ds_write_b32 v0, v8 offset:2080
	s_waitcnt vmcnt(12)
	ds_write_b32 v0, v9 offset:3120
	s_waitcnt vmcnt(11)
	ds_write_b32 v0, v10 offset:4160
	s_waitcnt vmcnt(10)
	ds_write_b32 v0, v11 offset:5200
	s_waitcnt vmcnt(9)
	ds_write_b32 v0, v12 offset:6240
	s_waitcnt vmcnt(8)
	ds_write_b32 v0, v13 offset:7280
	s_waitcnt vmcnt(7)
	ds_write_b32 v0, v14 offset:8320
	s_waitcnt vmcnt(6)
	ds_write_b32 v0, v15 offset:9360
	s_waitcnt vmcnt(5)
	ds_write_b32 v0, v16 offset:10400
	s_waitcnt vmcnt(4)
	ds_write_b32 v0, v17 offset:11440
	s_waitcnt vmcnt(3)
	ds_write_b32 v0, v18 offset:12480
	s_waitcnt vmcnt(2)
	ds_write_b32 v0, v19 offset:13520
	s_waitcnt vmcnt(1)
	ds_write_b32 v0, v4 offset:14560
	s_waitcnt vmcnt(0)
	ds_write_b32 v0, v5 offset:15600
	s_waitcnt lgkmcnt(0)
	s_barrier

; __device__ __forceinline__ void conv_tile(const float* __restrict__ src, int ld, int col0, int nvalid, int K, u16* __restrict__ dst,
;                           int tile, float* T) {
;   const int ktiles = K >> 6;
;   const int kt = tile % ktiles, nt = tile / ktiles;
;   const int k0 = kt * 64, n0 = nt * 64;
;   const int tid = TID(), tx = tid & 63, ty = tid >> 6;
;   __syncthreads();
;   float tv[16];
; #pragma unroll
;   for (int r = 0; r < 16; r++) {
;     tv[r] = 0.f;
;     if (n0 + tx < nvalid) tv[r] = src[(size_t)(k0 + ty + 4 * r) * ld + col0 + n0 + tx];
;   }
; #pragma unroll
;   for (int r = 0; r < 16; r++) T[(ty + 4 * r) * 65 + tx] = tv[r];
;   __syncthreads();
; __device__ __forceinline__ void convert_weights(const Params& P, int l, float* T) {
;     ...
;     else if (t < c7) conv_tile(P.mla_w_uq + (size_t)l * 256 * 384, 384, 0, 384, 256, (u16*)(ws + O_WUQ), t - c6, T);
.LBB0_2450:
	s_and_b32 s0, s52, 0xfc0
	s_xor_b32 s0, s0, 0x800
	s_and_b32 s1, s53, 0xc0
	v_mov_b32_e32 v2, v169
	s_lshl_b32 s2, s0, 2
	s_add_u32 s2, s31, s2
	v_lshlrev_b32_e32 v0, 2, v2
	v_ashrrev_i32_e32 v3, 6, v2
	s_addc_u32 s3, s34, 0
	v_and_b32_e32 v130, 0xfc, v0
	v_add_u32_e32 v6, s1, v3
	v_lshl_add_u64 v[0:1], s[2:3], 0, v[130:131]
	s_movk_i32 s4, 0x600
	v_mad_i64_i32 v[4:5], s[2:3], v6, s4, v[0:1]
	s_barrier
	global_load_dword v7, v[4:5], off nt
	v_add_u32_e32 v4, 4, v6
	v_mad_i64_i32 v[4:5], s[2:3], v4, s4, v[0:1]
	global_load_dword v8, v[4:5], off nt
	v_add_u32_e32 v4, 8, v6
	v_mad_i64_i32 v[4:5], s[2:3], v4, s4, v[0:1]
	global_load_dword v9, v[4:5], off nt
	v_add_u32_e32 v4, 12, v6
	v_mad_i64_i32 v[4:5], s[2:3], v4, s4, v[0:1]
	global_load_dword v10, v[4:5], off nt
	v_add_u32_e32 v4, 16, v6
	v_mad_i64_i32 v[4:5], s[2:3], v4, s4, v[0:1]
	global_load_dword v11, v[4:5], off nt
	v_add_u32_e32 v4, 20, v6
	v_mad_i64_i32 v[4:5], s[2:3], v4, s4, v[0:1]
	global_load_dword v12, v[4:5], off nt
	v_add_u32_e32 v4, 24, v6
	v_mad_i64_i32 v[4:5], s[2:3], v4, s4, v[0:1]
	global_load_dword v13, v[4:5], off nt
	v_add_u32_e32 v4, 28, v6
	v_mad_i64_i32 v[4:5], s[2:3], v4, s4, v[0:1]
	global_load_dword v14, v[4:5], off nt
	v_add_u32_e32 v4, 32, v6
	v_mad_i64_i32 v[4:5], s[2:3], v4, s4, v[0:1]
	global_load_dword v15, v[4:5], off nt
	v_add_u32_e32 v4, 36, v6
	v_mad_i64_i32 v[4:5], s[2:3], v4, s4, v[0:1]
	global_load_dword v16, v[4:5], off nt
	v_add_u32_e32 v4, 40, v6
	v_mad_i64_i32 v[4:5], s[2:3], v4, s4, v[0:1]
	global_load_dword v17, v[4:5], off nt
	v_add_u32_e32 v4, 44, v6
	v_mad_i64_i32 v[4:5], s[2:3], v4, s4, v[0:1]
	global_load_dword v18, v[4:5], off nt
	v_add_u32_e32 v4, 48, v6
	v_mad_i64_i32 v[4:5], s[2:3], v4, s4, v[0:1]
	global_load_dword v19, v[4:5], off nt
	v_add_u32_e32 v4, 52, v6
	v_mad_i64_i32 v[4:5], s[2:3], v4, s4, v[0:1]
	global_load_dword v20, v[4:5], off nt
	v_add_u32_e32 v4, 56, v6
	v_mad_i64_i32 v[4:5], s[2:3], v4, s4, v[0:1]
	global_load_dword v4, v[4:5], off nt
	v_add_u32_e32 v5, 60, v6
	v_mad_i64_i32 v[0:1], s[2:3], v5, s4, v[0:1]
	global_load_dword v5, v[0:1], off nt
	s_movk_i32 s2, 0x104
	v_mad_u64_u32 v[0:1], s[2:3], v3, s2, v[130:131]
	s_lshl_b32 s1, s1, 1
	s_add_u32 s2, s16, s1
	s_addc_u32 s3, s17, 0
	s_mov_b64 s[4:5], 9
	s_waitcnt vmcnt(15)
	ds_write_b32 v0, v7
	s_waitcnt vmcnt(14)
	ds_write_b32 v0, v8 offset:1040
	s_waitcnt vmcnt(13)
	ds_write_b32 v0, v9 offset:2080
	s_waitcnt vmcnt(12)
	ds_write_b32 v0, v10 offset:3120
	s_waitcnt vmcnt(11)
	ds_write_b32 v0, v11 offset:4160
	s_waitcnt vmcnt(10)
	ds_write_b32 v0, v12 offset:5200
	s_waitcnt vmcnt(9)
	ds_write_b32 v0, v13 offset:6240
	s_waitcnt vmcnt(8)
	ds_write_b32 v0, v14 offset:7280
	s_waitcnt vmcnt(7)
	ds_write_b32 v0, v15 offset:8320
	s_waitcnt vmcnt(6)
	ds_write_b32 v0, v16 offset:9360
	s_waitcnt vmcnt(5)
	ds_write_b32 v0, v17 offset:10400
	s_waitcnt vmcnt(4)
	ds_write_b32 v0, v18 offset:11440
	s_waitcnt vmcnt(3)
	ds_write_b32 v0, v19 offset:12480
	s_waitcnt vmcnt(2)
	ds_write_b32 v0, v20 offset:13520
	s_waitcnt vmcnt(1)
	ds_write_b32 v0, v4 offset:14560
	s_waitcnt vmcnt(0)
	ds_write_b32 v0, v5 offset:15600
	s_waitcnt lgkmcnt(0)
	s_barrier

; __device__ __forceinline__ void conv_tile(const float* __restrict__ src, int ld, int col0, int nvalid, int K, u16* __restrict__ dst,
;                           int tile, float* T) {
;     ...
;   __syncthreads();
;   float tv[16];
; #pragma unroll
;   for (int r = 0; r < 16; r++) {
;     tv[r] = 0.f;
;     if (n0 + tx < nvalid) tv[r] = src[(size_t)(k0 + ty + 4 * r) * ld + col0 + n0 + tx];
;   }
; #pragma unroll
;   for (int r = 0; r < 16; r++) T[(ty + 4 * r) * 65 + tx] = tv[r];
;   __syncthreads();
; __device__ __forceinline__ void convert_weights(const Params& P, int l, float* T) {
;     ...
;     else if (t < c6) conv_tile(P.mlp_w2 + (size_t)l * 4096 * 1024, 1024, 0, 1024, 4096, (u16*)(ws + O_W2), t - c5, T);
.LBB0_2452:
	s_add_i32 s0, s59, 0xf380
	s_and_b32 s0, s0, 0xffc0
	v_mov_b32_e32 v2, v169
	s_and_b32 s1, s53, 0xfc0
	s_lshl_b32 s2, s0, 2
	v_ashrrev_i32_e32 v3, 6, v2
	v_add_u32_e32 v0, s1, v3
	s_add_u32 s2, s35, s2
	v_lshlrev_b32_e32 v1, 2, v2
	s_addc_u32 s3, s36, 0
	v_and_b32_e32 v130, 0xfc, v1
	v_ashrrev_i32_e32 v1, 31, v0
	v_lshl_add_u64 v[4:5], s[2:3], 0, v[130:131]
	v_lshlrev_b64 v[0:1], 12, v[0:1]
	v_lshl_add_u64 v[0:1], v[4:5], 0, v[0:1]
	v_add_co_u32_e32 v4, vcc, s61, v0
	s_mov_b32 s2, 0x8000
	s_nop 0
	v_addc_co_u32_e32 v5, vcc, 0, v1, vcc
	s_barrier
	global_load_dword v6, v[0:1], off nt
	global_load_dword v7, v[4:5], off nt
	v_add_co_u32_e32 v4, vcc, s2, v0
	s_mov_b32 s2, 0xc000
	s_nop 0
	v_addc_co_u32_e32 v5, vcc, 0, v1, vcc
	global_load_dword v8, v[4:5], off nt
	v_add_co_u32_e32 v4, vcc, s2, v0
	s_mov_b32 s2, 0x14000
	s_nop 0
	v_addc_co_u32_e32 v5, vcc, 0, v1, vcc
	global_load_dword v9, v[4:5], off nt
	v_add_co_u32_e32 v4, vcc, s33, v0
	s_lshl_b32 s1, s1, 1
	s_nop 0
	v_addc_co_u32_e32 v5, vcc, 0, v1, vcc
	global_load_dword v10, v[4:5], off nt
	v_add_co_u32_e32 v4, vcc, s2, v0
	s_mov_b32 s2, 0x18000
	s_nop 0
	v_addc_co_u32_e32 v5, vcc, 0, v1, vcc
	global_load_dword v11, v[4:5], off nt
	v_add_co_u32_e32 v4, vcc, s2, v0
	s_mov_b32 s2, 0x1c000
	s_nop 0
	v_addc_co_u32_e32 v5, vcc, 0, v1, vcc
	global_load_dword v12, v[4:5], off nt
	v_add_co_u32_e32 v4, vcc, s2, v0
	s_mov_b32 s2, 0x24000
	s_nop 0
	v_addc_co_u32_e32 v5, vcc, 0, v1, vcc
	global_load_dword v13, v[4:5], off nt
	v_add_co_u32_e32 v4, vcc, s56, v0
	s_mov_b64 s[4:5], 13
	s_nop 0
	v_addc_co_u32_e32 v5, vcc, 0, v1, vcc
	global_load_dword v14, v[4:5], off nt
	v_add_co_u32_e32 v4, vcc, s2, v0
	s_mov_b32 s2, 0x28000
	s_nop 0
	v_addc_co_u32_e32 v5, vcc, 0, v1, vcc
	global_load_dword v15, v[4:5], off nt
	v_add_co_u32_e32 v4, vcc, s2, v0
	s_mov_b32 s2, 0x2c000
	s_nop 0
	v_addc_co_u32_e32 v5, vcc, 0, v1, vcc
	global_load_dword v16, v[4:5], off nt
	v_add_co_u32_e32 v4, vcc, s2, v0
	s_mov_b32 s2, 0x34000
	s_nop 0
	v_addc_co_u32_e32 v5, vcc, 0, v1, vcc
	global_load_dword v17, v[4:5], off nt
	v_add_co_u32_e32 v4, vcc, s57, v0
	s_nop 1
	v_addc_co_u32_e32 v5, vcc, 0, v1, vcc
	global_load_dword v18, v[4:5], off nt
	v_add_co_u32_e32 v4, vcc, s2, v0
	s_mov_b32 s2, 0x38000
	s_nop 0
	v_addc_co_u32_e32 v5, vcc, 0, v1, vcc
	global_load_dword v19, v[4:5], off nt
	v_add_co_u32_e32 v4, vcc, s2, v0
	s_mov_b32 s2, 0x3c000
	s_nop 0
	v_addc_co_u32_e32 v5, vcc, 0, v1, vcc
	v_add_co_u32_e32 v0, vcc, s2, v0
	global_load_dword v4, v[4:5], off nt
	s_nop 0
	v_addc_co_u32_e32 v1, vcc, 0, v1, vcc
	global_load_dword v5, v[0:1], off nt
	s_movk_i32 s2, 0x104
	v_mad_u64_u32 v[0:1], s[2:3], v3, s2, v[130:131]
	s_add_u32 s2, s18, s1
	s_addc_u32 s3, s19, 0
	s_waitcnt vmcnt(15)
	ds_write_b32 v0, v6
	s_waitcnt vmcnt(14)
	ds_write_b32 v0, v7 offset:1040
	s_waitcnt vmcnt(13)
	ds_write_b32 v0, v8 offset:2080
	s_waitcnt vmcnt(12)
	ds_write_b32 v0, v9 offset:3120
	s_waitcnt vmcnt(11)
	ds_write_b32 v0, v10 offset:4160
	s_waitcnt vmcnt(10)
	ds_write_b32 v0, v11 offset:5200
	s_waitcnt vmcnt(9)
	ds_write_b32 v0, v12 offset:6240
	s_waitcnt vmcnt(8)
	ds_write_b32 v0, v13 offset:7280
	s_waitcnt vmcnt(7)
	ds_write_b32 v0, v14 offset:8320
	s_waitcnt vmcnt(6)
	ds_write_b32 v0, v15 offset:9360
	s_waitcnt vmcnt(5)
	ds_write_b32 v0, v16 offset:10400
	s_waitcnt vmcnt(4)
	ds_write_b32 v0, v17 offset:11440
	s_waitcnt vmcnt(3)
	ds_write_b32 v0, v18 offset:12480
	s_waitcnt vmcnt(2)
	ds_write_b32 v0, v19 offset:13520
	s_waitcnt vmcnt(1)
	ds_write_b32 v0, v4 offset:14560
	s_waitcnt vmcnt(0)
	ds_write_b32 v0, v5 offset:15600
	s_waitcnt lgkmcnt(0)
	s_barrier

; __device__ __forceinline__ void conv_tile(const float* __restrict__ src, int ld, int col0, int nvalid, int K, u16* __restrict__ dst,
;                           int tile, float* T) {
;     ...
;   __syncthreads();
;   float tv[16];
; #pragma unroll
;   for (int r = 0; r < 16; r++) {
;     tv[r] = 0.f;
;     if (n0 + tx < nvalid) tv[r] = src[(size_t)(k0 + ty + 4 * r) * ld + col0 + n0 + tx];
;   }
; #pragma unroll
;   for (int r = 0; r < 16; r++) T[(ty + 4 * r) * 65 + tx] = tv[r];
;   __syncthreads();
; __device__ __forceinline__ void convert_weights(const Params& P, int l, float* T) {
;     ...
;     else if (t < c5) conv_tile(P.mlp_w1 + (size_t)l * 1024 * 4096, 4096, 0, 4096, 1024, (u16*)(ws + O_W1), t - c4, T);
.LBB0_2454:
	s_add_i32 s0, s50, 0x3de00
	s_and_b32 s0, s0, 0x3ffc0
	v_mov_b32_e32 v2, v169
	s_and_b32 s1, s53, 0x3c0
	s_lshl_b32 s2, s0, 2
	v_ashrrev_i32_e32 v3, 6, v2
	v_add_u32_e32 v0, s1, v3
	s_add_u32 s2, s37, s2
	v_lshlrev_b32_e32 v1, 2, v2
	s_addc_u32 s3, s38, 0
	v_and_b32_e32 v130, 0xfc, v1
	v_ashrrev_i32_e32 v1, 31, v0
	v_lshl_add_u64 v[4:5], s[2:3], 0, v[130:131]
	v_lshlrev_b64 v[0:1], 14, v[0:1]
	v_lshl_add_u64 v[0:1], v[4:5], 0, v[0:1]
	v_add_co_u32_e32 v4, vcc, s33, v0
	s_nop 1
	v_addc_co_u32_e32 v5, vcc, 0, v1, vcc
	s_barrier
	global_load_dword v6, v[0:1], off nt
	global_load_dword v7, v[4:5], off nt
	v_add_co_u32_e32 v4, vcc, s56, v0
	s_mov_b32 s2, 0x50000
	s_nop 0
	v_addc_co_u32_e32 v5, vcc, 0, v1, vcc
	global_load_dword v8, v[4:5], off nt
	v_add_co_u32_e32 v4, vcc, s57, v0
	s_lshl_b32 s1, s1, 1
	s_nop 0
	v_addc_co_u32_e32 v5, vcc, 0, v1, vcc
	global_load_dword v9, v[4:5], off nt
	v_add_co_u32_e32 v4, vcc, s94, v0
	s_mov_b64 s[4:5], 11
	s_nop 0
	v_addc_co_u32_e32 v5, vcc, 0, v1, vcc
	global_load_dword v10, v[4:5], off nt
	v_add_co_u32_e32 v4, vcc, s2, v0
	s_mov_b32 s2, 0x60000
	s_nop 0
	v_addc_co_u32_e32 v5, vcc, 0, v1, vcc
	global_load_dword v11, v[4:5], off nt
	v_add_co_u32_e32 v4, vcc, s2, v0
	s_mov_b32 s2, 0x70000
	s_nop 0
	v_addc_co_u32_e32 v5, vcc, 0, v1, vcc
	global_load_dword v12, v[4:5], off nt
	v_add_co_u32_e32 v4, vcc, s2, v0
	s_mov_b32 s2, 0x80000
	s_nop 0
	v_addc_co_u32_e32 v5, vcc, 0, v1, vcc
	global_load_dword v13, v[4:5], off nt
	v_add_co_u32_e32 v4, vcc, s2, v0
	s_mov_b32 s2, 0x90000
	s_nop 0
	v_addc_co_u32_e32 v5, vcc, 0, v1, vcc
	global_load_dword v14, v[4:5], off nt
	v_add_co_u32_e32 v4, vcc, s2, v0
	s_mov_b32 s2, 0xa0000
	s_nop 0
	v_addc_co_u32_e32 v5, vcc, 0, v1, vcc
	global_load_dword v15, v[4:5], off nt
	v_add_co_u32_e32 v4, vcc, s2, v0
	s_mov_b32 s2, 0xb0000
	s_nop 0
	v_addc_co_u32_e32 v5, vcc, 0, v1, vcc
	global_load_dword v16, v[4:5], off nt
	v_add_co_u32_e32 v4, vcc, s2, v0
	s_mov_b32 s2, 0xd0000
	s_nop 0
	v_addc_co_u32_e32 v5, vcc, 0, v1, vcc
	global_load_dword v17, v[4:5], off nt
	v_add_co_u32_e32 v4, vcc, s97, v0
	s_nop 1
	v_addc_co_u32_e32 v5, vcc, 0, v1, vcc
	global_load_dword v18, v[4:5], off nt
	v_add_co_u32_e32 v4, vcc, s2, v0
	s_mov_b32 s2, 0xe0000
	s_nop 0
	v_addc_co_u32_e32 v5, vcc, 0, v1, vcc
	global_load_dword v19, v[4:5], off nt
	v_add_co_u32_e32 v4, vcc, s2, v0
	s_mov_b32 s2, 0xf0000
	s_nop 0
	v_addc_co_u32_e32 v5, vcc, 0, v1, vcc
	v_add_co_u32_e32 v0, vcc, s2, v0
	global_load_dword v4, v[4:5], off nt
	s_nop 0
	v_addc_co_u32_e32 v1, vcc, 0, v1, vcc
	global_load_dword v5, v[0:1], off nt
	s_movk_i32 s2, 0x104
	v_mad_u64_u32 v[0:1], s[2:3], v3, s2, v[130:131]
	s_add_u32 s2, s20, s1
	s_addc_u32 s3, s21, 0
	s_waitcnt vmcnt(15)
	ds_write_b32 v0, v6
	s_waitcnt vmcnt(14)
	ds_write_b32 v0, v7 offset:1040
	s_waitcnt vmcnt(13)
	ds_write_b32 v0, v8 offset:2080
	s_waitcnt vmcnt(12)
	ds_write_b32 v0, v9 offset:3120
	s_waitcnt vmcnt(11)
	ds_write_b32 v0, v10 offset:4160
	s_waitcnt vmcnt(10)
	ds_write_b32 v0, v11 offset:5200
	s_waitcnt vmcnt(9)
	ds_write_b32 v0, v12 offset:6240
	s_waitcnt vmcnt(8)
	ds_write_b32 v0, v13 offset:7280
	s_waitcnt vmcnt(7)
	ds_write_b32 v0, v14 offset:8320
	s_waitcnt vmcnt(6)
	ds_write_b32 v0, v15 offset:9360
	s_waitcnt vmcnt(5)
	ds_write_b32 v0, v16 offset:10400
	s_waitcnt vmcnt(4)
	ds_write_b32 v0, v17 offset:11440
	s_waitcnt vmcnt(3)
	ds_write_b32 v0, v18 offset:12480
	s_waitcnt vmcnt(2)
	ds_write_b32 v0, v19 offset:13520
	s_waitcnt vmcnt(1)
	ds_write_b32 v0, v4 offset:14560
	s_waitcnt vmcnt(0)
	ds_write_b32 v0, v5 offset:15600
	s_waitcnt lgkmcnt(0)
	s_barrier

; __device__ __forceinline__ void conv_tile(const float* __restrict__ src, int ld, int col0, int nvalid, int K, u16* __restrict__ dst,
;                           int tile, float* T) {
;     ...
;   __syncthreads();
;   float tv[16];
; #pragma unroll
;   for (int r = 0; r < 16; r++) {
;     tv[r] = 0.f;
;     if (n0 + tx < nvalid) tv[r] = src[(size_t)(k0 + ty + 4 * r) * ld + col0 + n0 + tx];
;   }
; #pragma unroll
;   for (int r = 0; r < 16; r++) T[(ty + 4 * r) * 65 + tx] = tv[r];
;   __syncthreads();
; __device__ __forceinline__ void convert_weights(const Params& P, int l, float* T) {
;     ...
;     } else if (t < c4) conv_tile(P.w_out + (size_t)l * 1024 * 1024, 1024, 0, 1024, 1024, (u16*)(ws + O_WO), t - c3, T);
.LBB0_2456:
	s_and_b32 s0, s50, 0x3c0
	s_xor_b32 s0, s0, 0x200
	v_mov_b32_e32 v2, v169
	s_and_b32 s1, s53, 0x3c0
	s_lshl_b32 s2, s0, 2
	v_ashrrev_i32_e32 v3, 6, v2
	v_add_u32_e32 v0, s1, v3
	s_add_u32 s2, s39, s2
	v_lshlrev_b32_e32 v1, 2, v2
	s_addc_u32 s3, s40, 0
	v_and_b32_e32 v130, 0xfc, v1
	v_ashrrev_i32_e32 v1, 31, v0
	v_lshl_add_u64 v[4:5], s[2:3], 0, v[130:131]
	v_lshlrev_b64 v[0:1], 12, v[0:1]
	v_lshl_add_u64 v[0:1], v[4:5], 0, v[0:1]
	v_add_co_u32_e32 v4, vcc, s61, v0
	s_mov_b32 s2, 0x8000
	s_nop 0
	v_addc_co_u32_e32 v5, vcc, 0, v1, vcc
	s_barrier
	global_load_dword v6, v[0:1], off nt
	global_load_dword v7, v[4:5], off nt
	v_add_co_u32_e32 v4, vcc, s2, v0
	s_mov_b32 s2, 0xc000
	s_nop 0
	v_addc_co_u32_e32 v5, vcc, 0, v1, vcc
	global_load_dword v8, v[4:5], off nt
	v_add_co_u32_e32 v4, vcc, s2, v0
	s_mov_b32 s2, 0x14000
	s_nop 0
	v_addc_co_u32_e32 v5, vcc, 0, v1, vcc
	global_load_dword v9, v[4:5], off nt
	v_add_co_u32_e32 v4, vcc, s33, v0
	s_lshl_b32 s1, s1, 1
	s_nop 0
	v_addc_co_u32_e32 v5, vcc, 0, v1, vcc
	global_load_dword v10, v[4:5], off nt
	v_add_co_u32_e32 v4, vcc, s2, v0
	s_mov_b32 s2, 0x18000
	s_nop 0
	v_addc_co_u32_e32 v5, vcc, 0, v1, vcc
	global_load_dword v11, v[4:5], off nt
	v_add_co_u32_e32 v4, vcc, s2, v0
	s_mov_b32 s2, 0x1c000
	s_nop 0
	v_addc_co_u32_e32 v5, vcc, 0, v1, vcc
	global_load_dword v12, v[4:5], off nt
	v_add_co_u32_e32 v4, vcc, s2, v0
	s_mov_b32 s2, 0x24000
	s_nop 0
	v_addc_co_u32_e32 v5, vcc, 0, v1, vcc
	global_load_dword v13, v[4:5], off nt
	v_add_co_u32_e32 v4, vcc, s56, v0
	s_mov_b64 s[4:5], 11
	s_nop 0
	v_addc_co_u32_e32 v5, vcc, 0, v1, vcc
	global_load_dword v14, v[4:5], off nt
	v_add_co_u32_e32 v4, vcc, s2, v0
	s_mov_b32 s2, 0x28000
	s_nop 0
	v_addc_co_u32_e32 v5, vcc, 0, v1, vcc
	global_load_dword v15, v[4:5], off nt
	v_add_co_u32_e32 v4, vcc, s2, v0
	s_mov_b32 s2, 0x2c000
	s_nop 0
	v_addc_co_u32_e32 v5, vcc, 0, v1, vcc
	global_load_dword v16, v[4:5], off nt
	v_add_co_u32_e32 v4, vcc, s2, v0
	s_mov_b32 s2, 0x34000
	s_nop 0
	v_addc_co_u32_e32 v5, vcc, 0, v1, vcc
	global_load_dword v17, v[4:5], off nt
	v_add_co_u32_e32 v4, vcc, s57, v0
	s_nop 1
	v_addc_co_u32_e32 v5, vcc, 0, v1, vcc
	global_load_dword v18, v[4:5], off nt
	v_add_co_u32_e32 v4, vcc, s2, v0
	s_mov_b32 s2, 0x38000
	s_nop 0
	v_addc_co_u32_e32 v5, vcc, 0, v1, vcc
	global_load_dword v19, v[4:5], off nt
	v_add_co_u32_e32 v4, vcc, s2, v0
	s_mov_b32 s2, 0x3c000
	s_nop 0
	v_addc_co_u32_e32 v5, vcc, 0, v1, vcc
	v_add_co_u32_e32 v0, vcc, s2, v0
	global_load_dword v4, v[4:5], off nt
	s_nop 0
	v_addc_co_u32_e32 v1, vcc, 0, v1, vcc
	global_load_dword v5, v[0:1], off nt
	s_movk_i32 s2, 0x104
	v_mad_u64_u32 v[0:1], s[2:3], v3, s2, v[130:131]
	s_add_u32 s2, s15, s1
	s_addc_u32 s3, s22, 0
	s_waitcnt vmcnt(15)
	ds_write_b32 v0, v6
	s_waitcnt vmcnt(14)
	ds_write_b32 v0, v7 offset:1040
	s_waitcnt vmcnt(13)
	ds_write_b32 v0, v8 offset:2080
	s_waitcnt vmcnt(12)
	ds_write_b32 v0, v9 offset:3120
	s_waitcnt vmcnt(11)
	ds_write_b32 v0, v10 offset:4160
	s_waitcnt vmcnt(10)
	ds_write_b32 v0, v11 offset:5200
	s_waitcnt vmcnt(9)
	ds_write_b32 v0, v12 offset:6240
	s_waitcnt vmcnt(8)
	ds_write_b32 v0, v13 offset:7280
	s_waitcnt vmcnt(7)
	ds_write_b32 v0, v14 offset:8320
	s_waitcnt vmcnt(6)
	ds_write_b32 v0, v15 offset:9360
	s_waitcnt vmcnt(5)
	ds_write_b32 v0, v16 offset:10400
	s_waitcnt vmcnt(4)
	ds_write_b32 v0, v17 offset:11440
	s_waitcnt vmcnt(3)
	ds_write_b32 v0, v18 offset:12480
	s_waitcnt vmcnt(2)
	ds_write_b32 v0, v19 offset:13520
	s_waitcnt vmcnt(1)
	ds_write_b32 v0, v4 offset:14560
	s_waitcnt vmcnt(0)
	ds_write_b32 v0, v5 offset:15600
	s_waitcnt lgkmcnt(0)
	s_barrier

; __device__ __forceinline__ void conv_tile(const float* __restrict__ src, int ld, int col0, int nvalid, int K, u16* __restrict__ dst,
;                           int tile, float* T) {
;     ...
;   __syncthreads();
;   float tv[16];
; #pragma unroll
;   for (int r = 0; r < 16; r++) {
;     tv[r] = 0.f;
;     if (n0 + tx < nvalid) tv[r] = src[(size_t)(k0 + ty + 4 * r) * ld + col0 + n0 + tx];
;   }
; #pragma unroll
;   for (int r = 0; r < 16; r++) T[(ty + 4 * r) * 65 + tx] = tv[r];
;   __syncthreads();
; __device__ __forceinline__ void convert_weights(const Params& P, int l, float* T) {
;     ...
;     else if (t < c3) {
;       int tt = t - c2, i = tt >> 6;
;       conv_tile(P.w_branch + ((size_t)l * 4 + i) * 256 * 1024, 1024, 0, 1024, 256, (u16*)(ws + O_WB) + (size_t)i * 1024 * 256, tt & 63, T);
.LBB0_2458:
	s_add_i32 s0, s59, 0xfffff980
	s_lshr_b32 s54, s0, 6
	s_lshl_b64 s[0:1], s[54:55], 20
	s_add_u32 s2, s41, s0
	s_addc_u32 s3, s42, s1
	s_lshl_b64 s[0:1], s[54:55], 19
	s_add_u32 s4, s23, s0
	s_addc_u32 s1, s24, s1
	s_and_b32 s0, s52, 0x3c0
	v_mov_b32_e32 v2, v169
	s_and_b32 s5, s53, 0xc0
	s_lshl_b32 s6, s0, 2
	v_ashrrev_i32_e32 v3, 6, v2
	v_add_u32_e32 v0, s5, v3
	s_add_u32 s2, s2, s6
	v_lshlrev_b32_e32 v1, 2, v2
	s_addc_u32 s3, s3, 0
	v_and_b32_e32 v130, 0xfc, v1
	v_ashrrev_i32_e32 v1, 31, v0
	v_lshl_add_u64 v[4:5], s[2:3], 0, v[130:131]
	v_lshlrev_b64 v[0:1], 12, v[0:1]
	v_lshl_add_u64 v[0:1], v[4:5], 0, v[0:1]
	v_add_co_u32_e32 v4, vcc, s61, v0
	s_mov_b32 s2, 0x8000
	s_nop 0
	v_addc_co_u32_e32 v5, vcc, 0, v1, vcc
	s_barrier
	global_load_dword v6, v[0:1], off nt
	global_load_dword v7, v[4:5], off nt
	v_add_co_u32_e32 v4, vcc, s2, v0
	s_mov_b32 s2, 0xc000
	s_nop 0
	v_addc_co_u32_e32 v5, vcc, 0, v1, vcc
	global_load_dword v8, v[4:5], off nt
	v_add_co_u32_e32 v4, vcc, s2, v0
	s_mov_b32 s2, 0x14000
	s_nop 0
	v_addc_co_u32_e32 v5, vcc, 0, v1, vcc
	global_load_dword v9, v[4:5], off nt
	v_add_co_u32_e32 v4, vcc, s33, v0
	s_nop 1
	v_addc_co_u32_e32 v5, vcc, 0, v1, vcc
	global_load_dword v10, v[4:5], off nt
	v_add_co_u32_e32 v4, vcc, s2, v0
	s_mov_b32 s2, 0x18000
	s_nop 0
	v_addc_co_u32_e32 v5, vcc, 0, v1, vcc
	global_load_dword v11, v[4:5], off nt
	v_add_co_u32_e32 v4, vcc, s2, v0
	s_mov_b32 s2, 0x1c000
	s_nop 0
	v_addc_co_u32_e32 v5, vcc, 0, v1, vcc
	global_load_dword v12, v[4:5], off nt
	v_add_co_u32_e32 v4, vcc, s2, v0
	s_mov_b32 s2, 0x24000
	s_nop 0
	v_addc_co_u32_e32 v5, vcc, 0, v1, vcc
	global_load_dword v13, v[4:5], off nt
	v_add_co_u32_e32 v4, vcc, s56, v0
	s_nop 1
	v_addc_co_u32_e32 v5, vcc, 0, v1, vcc
	global_load_dword v14, v[4:5], off nt
	v_add_co_u32_e32 v4, vcc, s2, v0
	s_mov_b32 s2, 0x28000
	s_nop 0
	v_addc_co_u32_e32 v5, vcc, 0, v1, vcc
	global_load_dword v15, v[4:5], off nt
	v_add_co_u32_e32 v4, vcc, s2, v0
	s_mov_b32 s2, 0x2c000
	s_nop 0
	v_addc_co_u32_e32 v5, vcc, 0, v1, vcc
	global_load_dword v16, v[4:5], off nt
	v_add_co_u32_e32 v4, vcc, s2, v0
	s_mov_b32 s2, 0x34000
	s_nop 0
	v_addc_co_u32_e32 v5, vcc, 0, v1, vcc
	global_load_dword v17, v[4:5], off nt
	v_add_co_u32_e32 v4, vcc, s57, v0
	s_nop 1
	v_addc_co_u32_e32 v5, vcc, 0, v1, vcc
	global_load_dword v18, v[4:5], off nt
	v_add_co_u32_e32 v4, vcc, s2, v0
	s_mov_b32 s2, 0x38000
	s_nop 0
	v_addc_co_u32_e32 v5, vcc, 0, v1, vcc
	global_load_dword v19, v[4:5], off nt
	v_add_co_u32_e32 v4, vcc, s2, v0
	s_mov_b32 s2, 0x3c000
	s_nop 0
	v_addc_co_u32_e32 v5, vcc, 0, v1, vcc
	v_add_co_u32_e32 v0, vcc, s2, v0
	global_load_dword v4, v[4:5], off nt
	s_nop 0
	v_addc_co_u32_e32 v1, vcc, 0, v1, vcc
	global_load_dword v5, v[0:1], off nt
	s_movk_i32 s2, 0x104
	v_mad_u64_u32 v[0:1], s[2:3], v3, s2, v[130:131]
	s_lshl_b32 s2, s5, 1
	s_add_u32 s2, s4, s2
	s_addc_u32 s3, s1, 0
	s_mov_b64 s[4:5], 9
	s_waitcnt vmcnt(15)
	ds_write_b32 v0, v6
	s_waitcnt vmcnt(14)
	ds_write_b32 v0, v7 offset:1040
	s_waitcnt vmcnt(13)
	ds_write_b32 v0, v8 offset:2080
	s_waitcnt vmcnt(12)
	ds_write_b32 v0, v9 offset:3120
	s_waitcnt vmcnt(11)
	ds_write_b32 v0, v10 offset:4160
	s_waitcnt vmcnt(10)
	ds_write_b32 v0, v11 offset:5200
	s_waitcnt vmcnt(9)
	ds_write_b32 v0, v12 offset:6240
	s_waitcnt vmcnt(8)
	ds_write_b32 v0, v13 offset:7280
	s_waitcnt vmcnt(7)
	ds_write_b32 v0, v14 offset:8320
	s_waitcnt vmcnt(6)
	ds_write_b32 v0, v15 offset:9360
	s_waitcnt vmcnt(5)
	ds_write_b32 v0, v16 offset:10400
	s_waitcnt vmcnt(4)
	ds_write_b32 v0, v17 offset:11440
	s_waitcnt vmcnt(3)
	ds_write_b32 v0, v18 offset:12480
	s_waitcnt vmcnt(2)
	ds_write_b32 v0, v19 offset:13520
	s_waitcnt vmcnt(1)
	ds_write_b32 v0, v4 offset:14560
	s_waitcnt vmcnt(0)
	ds_write_b32 v0, v5 offset:15600
	s_waitcnt lgkmcnt(0)
	s_barrier

; __device__ __forceinline__ void conv_tile(const float* __restrict__ src, int ld, int col0, int nvalid, int K, u16* __restrict__ dst,
;                           int tile, float* T) {
;     ...
;   __syncthreads();
;   float tv[16];
; #pragma unroll
;   for (int r = 0; r < 16; r++) {
;     tv[r] = 0.f;
;     if (n0 + tx < nvalid) tv[r] = src[(size_t)(k0 + ty + 4 * r) * ld + col0 + n0 + tx];
;   }
; #pragma unroll
;   for (int r = 0; r < 16; r++) T[(ty + 4 * r) * 65 + tx] = tv[r];
;   __syncthreads();
; __device__ __forceinline__ void convert_weights(const Params& P, int l, float* T) {
;     ...
;     else if (t < c2) conv_tile(P.w_in + (size_t)l * 1024 * 6576, 6576, 2480, 4096, 1024, (u16*)(ws + O_WG), t - c1, T);
.LBB0_2460:
	s_add_i32 s0, s50, 0x3f600
	s_and_b32 s0, s0, 0x3ffc0
	s_and_b32 s1, s53, 0x3c0
	v_mov_b32_e32 v2, v169
	s_lshl_b32 s2, s0, 2
	s_add_u32 s2, s45, s2
	v_lshlrev_b32_e32 v0, 2, v2
	v_ashrrev_i32_e32 v3, 6, v2
	s_addc_u32 s3, s46, 0
	v_and_b32_e32 v130, 0xfc, v0
	v_add_u32_e32 v6, s1, v3
	v_lshl_add_u64 v[0:1], s[2:3], 0, v[130:131]
	s_movk_i32 s4, 0x66c0
	v_mad_i64_i32 v[4:5], s[2:3], v6, s4, v[0:1]
	s_barrier
	global_load_dword v7, v[4:5], off nt
	v_add_u32_e32 v4, 4, v6
	v_mad_i64_i32 v[4:5], s[2:3], v4, s4, v[0:1]
	global_load_dword v8, v[4:5], off nt
	v_add_u32_e32 v4, 8, v6
	v_mad_i64_i32 v[4:5], s[2:3], v4, s4, v[0:1]
	global_load_dword v9, v[4:5], off nt
	v_add_u32_e32 v4, 12, v6
	v_mad_i64_i32 v[4:5], s[2:3], v4, s4, v[0:1]
	global_load_dword v10, v[4:5], off nt
	v_add_u32_e32 v4, 16, v6
	v_mad_i64_i32 v[4:5], s[2:3], v4, s4, v[0:1]
	global_load_dword v11, v[4:5], off nt
	v_add_u32_e32 v4, 20, v6
	v_mad_i64_i32 v[4:5], s[2:3], v4, s4, v[0:1]
	global_load_dword v12, v[4:5], off nt
	v_add_u32_e32 v4, 24, v6
	v_mad_i64_i32 v[4:5], s[2:3], v4, s4, v[0:1]
	global_load_dword v13, v[4:5], off nt
	v_add_u32_e32 v4, 28, v6
	v_mad_i64_i32 v[4:5], s[2:3], v4, s4, v[0:1]
	global_load_dword v14, v[4:5], off nt
	v_add_u32_e32 v4, 32, v6
	v_mad_i64_i32 v[4:5], s[2:3], v4, s4, v[0:1]
	global_load_dword v15, v[4:5], off nt
	v_add_u32_e32 v4, 36, v6
	v_mad_i64_i32 v[4:5], s[2:3], v4, s4, v[0:1]
	global_load_dword v16, v[4:5], off nt
	v_add_u32_e32 v4, 40, v6
	v_mad_i64_i32 v[4:5], s[2:3], v4, s4, v[0:1]
	global_load_dword v17, v[4:5], off nt
	v_add_u32_e32 v4, 44, v6
	v_mad_i64_i32 v[4:5], s[2:3], v4, s4, v[0:1]
	global_load_dword v18, v[4:5], off nt
	v_add_u32_e32 v4, 48, v6
	v_mad_i64_i32 v[4:5], s[2:3], v4, s4, v[0:1]
	global_load_dword v19, v[4:5], off nt
	v_add_u32_e32 v4, 52, v6
	v_mad_i64_i32 v[4:5], s[2:3], v4, s4, v[0:1]
	global_load_dword v20, v[4:5], off nt
	v_add_u32_e32 v4, 56, v6
	v_mad_i64_i32 v[4:5], s[2:3], v4, s4, v[0:1]
	global_load_dword v4, v[4:5], off nt
	v_add_u32_e32 v5, 60, v6
	v_mad_i64_i32 v[0:1], s[2:3], v5, s4, v[0:1]
	global_load_dword v5, v[0:1], off nt
	s_movk_i32 s2, 0x104
	v_mad_u64_u32 v[0:1], s[2:3], v3, s2, v[130:131]
	s_lshl_b32 s1, s1, 1
	s_add_u32 s2, s25, s1
	s_addc_u32 s3, s26, 0
	s_mov_b64 s[4:5], 11
	s_waitcnt vmcnt(15)
	ds_write_b32 v0, v7
	s_waitcnt vmcnt(14)
	ds_write_b32 v0, v8 offset:1040
	s_waitcnt vmcnt(13)
	ds_write_b32 v0, v9 offset:2080
	s_waitcnt vmcnt(12)
	ds_write_b32 v0, v10 offset:3120
	s_waitcnt vmcnt(11)
	ds_write_b32 v0, v11 offset:4160
	s_waitcnt vmcnt(10)
	ds_write_b32 v0, v12 offset:5200
	s_waitcnt vmcnt(9)
	ds_write_b32 v0, v13 offset:6240
	s_waitcnt vmcnt(8)
	ds_write_b32 v0, v14 offset:7280
	s_waitcnt vmcnt(7)
	ds_write_b32 v0, v15 offset:8320
	s_waitcnt vmcnt(6)
	ds_write_b32 v0, v16 offset:9360
	s_waitcnt vmcnt(5)
	ds_write_b32 v0, v17 offset:10400
	s_waitcnt vmcnt(4)
	ds_write_b32 v0, v18 offset:11440
	s_waitcnt vmcnt(3)
	ds_write_b32 v0, v19 offset:12480
	s_waitcnt vmcnt(2)
	ds_write_b32 v0, v20 offset:13520
	s_waitcnt vmcnt(1)
	ds_write_b32 v0, v4 offset:14560
	s_waitcnt vmcnt(0)
	ds_write_b32 v0, v5 offset:15600
	s_waitcnt lgkmcnt(0)
	s_barrier

; __device__ __forceinline__ void conv_tile(const float* __restrict__ src, int ld, int col0, int nvalid, int K, u16* __restrict__ dst,
;                           int tile, float* T) {
;     ...
;   __syncthreads();
;   float tv[16];
; #pragma unroll
;   for (int r = 0; r < 16; r++) {
;     tv[r] = 0.f;
;     if (n0 + tx < nvalid) tv[r] = src[(size_t)(k0 + ty + 4 * r) * ld + col0 + n0 + tx];
; __device__ __forceinline__ void convert_weights(const Params& P, int l, float* T) {
;     ...
;     if (t < c1) conv_tile(P.w_in + (size_t)l * 1024 * 6576, 6576, 0, 2480, 1024, (u16*)(ws + O_WINA), t, T);
.LBB0_2462:
	s_ashr_i32 s0, s59, 31
	s_lshr_b32 s0, s0, 28
	s_add_i32 s0, s59, s0
	s_ashr_i32 s1, s0, 4
	v_mov_b32_e32 v2, v169
	s_lshl_b32 s0, s1, 6
	s_movk_i32 s2, 0x9b0
	v_and_b32_e32 v3, 63, v2
	v_or_b32_e32 v0, s0, v3
	s_lshl_b32 s4, s1, 10
	s_ashr_i32 s1, s0, 31
	v_cmp_gt_i32_e32 vcc, s2, v0
	s_lshl_b64 s[2:3], s[0:1], 2
	v_ashrrev_i32_e32 v4, 6, v2
	s_add_u32 s2, s43, s2
	v_subrev_u32_e32 v0, s4, v4
	s_addc_u32 s3, s44, s3
	v_lshlrev_b32_e32 v130, 2, v3
	v_add_u32_e32 v5, s53, v0
	v_lshl_add_u64 v[0:1], s[2:3], 0, v[130:131]
	v_mov_b32_e32 v6, 0
	v_mov_b32_e32 v7, 0
	s_barrier
	s_and_saveexec_b64 s[2:3], vcc
	s_cbranch_execz .LBB0_2464
	s_movk_i32 s1, 0x66c0
	v_mad_i64_i32 v[8:9], s[6:7], v5, s1, v[0:1]
	global_load_dword v7, v[8:9], off nt
.LBB0_2464:
	s_or_b64 exec, exec, s[2:3]
	s_and_saveexec_b64 s[2:3], vcc
	s_cbranch_execz .LBB0_2466
	v_add_u32_e32 v6, 4, v5
	s_movk_i32 s1, 0x66c0
	v_mad_i64_i32 v[8:9], s[6:7], v6, s1, v[0:1]
	global_load_dword v6, v[8:9], off nt
.LBB0_2466:
	s_or_b64 exec, exec, s[2:3]
	v_mov_b32_e32 v8, 0
	v_mov_b32_e32 v9, 0
	s_and_saveexec_b64 s[2:3], vcc
	s_cbranch_execz .LBB0_2468
	v_add_u32_e32 v9, 8, v5
	s_movk_i32 s1, 0x66c0
	v_mad_i64_i32 v[10:11], s[6:7], v9, s1, v[0:1]
	global_load_dword v9, v[10:11], off nt
.LBB0_2468:
	s_or_b64 exec, exec, s[2:3]
	s_and_saveexec_b64 s[2:3], vcc
	s_cbranch_execz .LBB0_2470
	v_add_u32_e32 v8, 12, v5
	s_movk_i32 s1, 0x66c0
	v_mad_i64_i32 v[10:11], s[6:7], v8, s1, v[0:1]
	global_load_dword v8, v[10:11], off nt
.LBB0_2470:
	s_or_b64 exec, exec, s[2:3]
	v_mov_b32_e32 v10, 0
	v_mov_b32_e32 v11, 0
	s_and_saveexec_b64 s[2:3], vcc
	s_cbranch_execz .LBB0_2472
	v_add_u32_e32 v11, 16, v5
	s_movk_i32 s1, 0x66c0
	v_mad_i64_i32 v[12:13], s[6:7], v11, s1, v[0:1]
	global_load_dword v11, v[12:13], off nt
.LBB0_2472:
	s_or_b64 exec, exec, s[2:3]
	s_and_saveexec_b64 s[2:3], vcc
	s_cbranch_execz .LBB0_2474
	v_add_u32_e32 v10, 20, v5
	s_movk_i32 s1, 0x66c0
	v_mad_i64_i32 v[12:13], s[6:7], v10, s1, v[0:1]
	global_load_dword v10, v[12:13], off nt
.LBB0_2474:
	s_or_b64 exec, exec, s[2:3]
	v_mov_b32_e32 v12, 0
	v_mov_b32_e32 v13, 0
	s_and_saveexec_b64 s[2:3], vcc
	s_cbranch_execz .LBB0_2476
	v_add_u32_e32 v13, 24, v5
	s_movk_i32 s1, 0x66c0
	v_mad_i64_i32 v[14:15], s[6:7], v13, s1, v[0:1]
	global_load_dword v13, v[14:15], off nt
.LBB0_2476:
	s_or_b64 exec, exec, s[2:3]
	s_and_saveexec_b64 s[2:3], vcc
	s_cbranch_execz .LBB0_2478
	v_add_u32_e32 v12, 28, v5
	s_movk_i32 s1, 0x66c0
	v_mad_i64_i32 v[14:15], s[6:7], v12, s1, v[0:1]
	global_load_dword v12, v[14:15], off nt
.LBB0_2478:
	s_or_b64 exec, exec, s[2:3]
	v_mov_b32_e32 v14, 0
	v_mov_b32_e32 v15, 0
	s_and_saveexec_b64 s[2:3], vcc
	s_cbranch_execz .LBB0_2480
	v_add_u32_e32 v15, 32, v5
	s_movk_i32 s1, 0x66c0
	v_mad_i64_i32 v[16:17], s[6:7], v15, s1, v[0:1]
	global_load_dword v15, v[16:17], off nt
.LBB0_2480:
	s_or_b64 exec, exec, s[2:3]
	s_and_saveexec_b64 s[2:3], vcc
	s_cbranch_execz .LBB0_2482
	v_add_u32_e32 v14, 36, v5
	s_movk_i32 s1, 0x66c0
	v_mad_i64_i32 v[16:17], s[6:7], v14, s1, v[0:1]
	global_load_dword v14, v[16:17], off nt
.LBB0_2482:
	s_or_b64 exec, exec, s[2:3]
	v_mov_b32_e32 v16, 0
	v_mov_b32_e32 v17, 0
	s_and_saveexec_b64 s[2:3], vcc
	s_cbranch_execz .LBB0_2484
	v_add_u32_e32 v17, 40, v5
	s_movk_i32 s1, 0x66c0
	v_mad_i64_i32 v[18:19], s[6:7], v17, s1, v[0:1]
	global_load_dword v17, v[18:19], off nt
.LBB0_2484:
	s_or_b64 exec, exec, s[2:3]
	s_and_saveexec_b64 s[2:3], vcc
	s_cbranch_execz .LBB0_2486
	v_add_u32_e32 v16, 44, v5
	s_movk_i32 s1, 0x66c0
	v_mad_i64_i32 v[18:19], s[6:7], v16, s1, v[0:1]
	global_load_dword v16, v[18:19], off nt
.LBB0_2486:
	s_or_b64 exec, exec, s[2:3]
	v_mov_b32_e32 v18, 0
	v_mov_b32_e32 v19, 0
	s_and_saveexec_b64 s[2:3], vcc
	s_cbranch_execz .LBB0_2488
	v_add_u32_e32 v19, 48, v5
	s_movk_i32 s1, 0x66c0
	v_mad_i64_i32 v[20:21], s[6:7], v19, s1, v[0:1]
	global_load_dword v19, v[20:21], off nt
.LBB0_2488:
	s_or_b64 exec, exec, s[2:3]
	s_and_saveexec_b64 s[2:3], vcc
	s_cbranch_execz .LBB0_2490
	v_add_u32_e32 v18, 52, v5
	s_movk_i32 s1, 0x66c0
	v_mad_i64_i32 v[20:21], s[6:7], v18, s1, v[0:1]
	global_load_dword v18, v[20:21], off nt
.LBB0_2490:
	s_or_b64 exec, exec, s[2:3]
	v_mov_b32_e32 v20, 0
	v_mov_b32_e32 v21, 0
	s_and_saveexec_b64 s[2:3], vcc
	s_cbranch_execz .LBB0_2492
	v_add_u32_e32 v21, 56, v5
	s_movk_i32 s1, 0x66c0
	v_mad_i64_i32 v[22:23], s[6:7], v21, s1, v[0:1]
	global_load_dword v21, v[22:23], off nt
.LBB0_2492:
	s_or_b64 exec, exec, s[2:3]
	s_and_saveexec_b64 s[2:3], vcc
	s_cbranch_execz .LBB0_2429
	v_add_u32_e32 v5, 60, v5
	s_movk_i32 s1, 0x66c0
	v_mad_i64_i32 v[0:1], s[6:7], v5, s1, v[0:1]
	global_load_dword v20, v[0:1], off nt
	s_branch .LBB0_2429
